# loop-edge edit: A-loop step-4 row-sum chain moved ahead of the loop-back barrier (on top of A DMA restructure + A VALU cleanup)
# baseline (speedup 1.0000x reference)
.LBB0_584:
.LBB0_586:
	v_pk_add_f32 v[166:167], v[186:187], v[166:167]
	s_nop 0
	v_pk_add_f32 v[166:167], v[168:169], v[166:167]
	s_nop 0
	v_pk_add_f32 v[120:121], v[120:121], v[166:167]
	s_nop 0
	v_pk_add_f32 v[120:121], v[122:123], v[120:121]
	s_nop 0
	v_pk_add_f32 v[120:121], v[124:125], v[120:121]
	s_nop 0
	v_pk_add_f32 v[100:101], v[100:101], v[120:121]
	s_nop 0
	v_pk_add_f32 v[100:101], v[104:105], v[100:101]
	v_pk_add_f32 v[104:105], v[112:113], v[184:185]
	v_pk_add_f32 v[186:187], v[108:109], v[100:101]
	v_pk_add_f32 v[104:105], v[114:115], v[104:105]
	s_nop 0
	v_pk_add_f32 v[104:105], v[116:117], v[104:105]
	s_nop 0
	v_pk_add_f32 v[104:105], v[118:119], v[104:105]
	s_nop 0
	v_pk_add_f32 v[96:97], v[96:97], v[104:105]
	s_nop 0
	v_pk_add_f32 v[96:97], v[98:99], v[96:97]
	s_nop 0
	v_pk_add_f32 v[96:97], v[102:103], v[96:97]
	s_nop 0
	v_pk_add_f32 v[184:185], v[106:107], v[96:97]
	s_waitcnt lgkmcnt(0)
	s_barrier
	v_max_f32_e32 v96, v110, v111
	v_cmp_lt_f32_e32 vcc, s96, v96
	s_cbranch_vccz .LBB0_554
	v_max_f32_e32 v32, v96, v96
	v_max_f32_e32 v33, 0, v32
	v_exp_f32_e64 v34, -v33
	v_add_f32_e32 v209, v209, v33
	v_xor_b32_e32 v32, 0x80000000, v209
	v_sub_f32_e32 v95, v95, v33
	v_sub_f32_e32 v94, v94, v33
	v_sub_f32_e32 v93, v93, v33
	v_sub_f32_e32 v92, v92, v33
	v_sub_f32_e32 v91, v91, v33
	v_sub_f32_e32 v90, v90, v33
	v_sub_f32_e32 v89, v89, v33
	v_sub_f32_e32 v88, v88, v33
	v_sub_f32_e32 v87, v87, v33
	v_sub_f32_e32 v86, v86, v33
	v_sub_f32_e32 v85, v85, v33
	v_sub_f32_e32 v84, v84, v33
	v_sub_f32_e32 v83, v83, v33
	v_sub_f32_e32 v82, v82, v33
	v_sub_f32_e32 v81, v81, v33
	v_sub_f32_e32 v80, v80, v33
	v_sub_f32_e32 v79, v79, v33
	v_sub_f32_e32 v78, v78, v33
	v_sub_f32_e32 v77, v77, v33
	v_sub_f32_e32 v76, v76, v33
	v_sub_f32_e32 v75, v75, v33
	v_sub_f32_e32 v74, v74, v33
	v_sub_f32_e32 v73, v73, v33
	v_sub_f32_e32 v72, v72, v33
	v_sub_f32_e32 v71, v71, v33
	v_sub_f32_e32 v70, v70, v33
	v_sub_f32_e32 v69, v69, v33
	v_sub_f32_e32 v68, v68, v33
	v_sub_f32_e32 v67, v67, v33
	v_sub_f32_e32 v66, v66, v33
	v_sub_f32_e32 v65, v65, v33
	v_sub_f32_e32 v64, v64, v33
	v_pk_mul_f32 v[14:15], v[14:15], v[34:35] op_sel_hi:[1,0]
	v_pk_mul_f32 v[12:13], v[12:13], v[34:35] op_sel_hi:[1,0]
	v_pk_mul_f32 v[10:11], v[10:11], v[34:35] op_sel_hi:[1,0]
	v_pk_mul_f32 v[8:9], v[8:9], v[34:35] op_sel_hi:[1,0]
	v_pk_mul_f32 v[6:7], v[6:7], v[34:35] op_sel_hi:[1,0]
	v_pk_mul_f32 v[4:5], v[4:5], v[34:35] op_sel_hi:[1,0]
	v_pk_mul_f32 v[2:3], v[2:3], v[34:35] op_sel_hi:[1,0]
	v_pk_mul_f32 v[0:1], v[0:1], v[34:35] op_sel_hi:[1,0]
	v_pk_mul_f32 v[30:31], v[30:31], v[34:35] op_sel_hi:[1,0]
	v_pk_mul_f32 v[28:29], v[28:29], v[34:35] op_sel_hi:[1,0]
	v_pk_mul_f32 v[26:27], v[26:27], v[34:35] op_sel_hi:[1,0]
	v_pk_mul_f32 v[24:25], v[24:25], v[34:35] op_sel_hi:[1,0]
	v_pk_mul_f32 v[22:23], v[22:23], v[34:35] op_sel_hi:[1,0]
	v_pk_mul_f32 v[20:21], v[20:21], v[34:35] op_sel_hi:[1,0]
	v_pk_mul_f32 v[18:19], v[18:19], v[34:35] op_sel_hi:[1,0]
	v_pk_mul_f32 v[16:17], v[16:17], v[34:35] op_sel_hi:[1,0]
	v_pk_mul_f32 v[184:185], v[184:185], v[34:35] op_sel_hi:[1,0]
	v_pk_mul_f32 v[186:187], v[186:187], v[34:35] op_sel_hi:[1,0]
	v_mov_b32_e32 v33, v32
	v_mov_b32_e32 v34, v32
	v_mov_b32_e32 v35, v32
	v_mov_b32_e32 v36, v32
	v_mov_b32_e32 v37, v32
	v_mov_b32_e32 v38, v32
	v_mov_b32_e32 v39, v32
	v_mov_b32_e32 v40, v32
	v_mov_b32_e32 v41, v32
	v_mov_b32_e32 v42, v32
	v_mov_b32_e32 v43, v32
	v_mov_b32_e32 v44, v32
	v_mov_b32_e32 v45, v32
	v_mov_b32_e32 v46, v32
	v_mov_b32_e32 v47, v32
	v_mov_b32_e32 v48, v32
	v_mov_b32_e32 v49, v32
	v_mov_b32_e32 v50, v32
	v_mov_b32_e32 v51, v32
	v_mov_b32_e32 v52, v32
	v_mov_b32_e32 v53, v32
	v_mov_b32_e32 v54, v32
	v_mov_b32_e32 v55, v32
	v_mov_b32_e32 v56, v32
	v_mov_b32_e32 v57, v32
	v_mov_b32_e32 v58, v32
	v_mov_b32_e32 v59, v32
	v_mov_b32_e32 v60, v32
	v_mov_b32_e32 v61, v32
	v_mov_b32_e32 v62, v32
	v_mov_b32_e32 v63, v32
	s_branch .LBB0_554
